# MLA fast loop: store addresses and K base of the next MFMA segment precomputed in the K.Q^T shadows (spare VGPRs), step-B ring rotation / counters moved from the P.V shadows to the K.Q^T shadows
# speedup vs baseline: 1.0068x; 1.0068x over previous
; #define ATT_BAR() do { asm volatile("s_waitcnt lgkmcnt(0)" ::: "memory"); __builtin_amdgcn_s_barrier(); asm volatile("" ::: "memory"); } while (0)
; template <int DK, int DV>
; __device__ __forceinline__ void attn_unit(LAS unsigned char* lds, const bf16* Qp, int ldq, const bf16* Kp, int ldk, const bf16* VTp, bf16* Op, int ldo, int qb) {
;     ...
;     ATT_QK(0, zacc);
;     if (grpB) ATT_BAR();
;     int bcur = 0, bnext = BUF, bfree = 2 * BUF;
; #pragma unroll 1
;     for (int t = 0; t < NT; t += 2) {
.Lfm_entry:
	s_mov_b32 s60, s58
	s_mov_b32 s58, s0
	v_add_u32_e32 v248, s58, v160
	ds_read_b128 v[164:167], v248 offset:13312
	ds_read_b128 v[168:171], v248 offset:17920
	ds_read_b128 v[172:175], v248 offset:13344
	ds_read_b128 v[176:179], v248 offset:17952
	ds_read_b128 v[180:183], v248 offset:13376
	ds_read_b128 v[220:223], v248 offset:17984
	ds_read_b128 v[224:227], v248 offset:13408
	ds_read_b128 v[232:235], v248 offset:18016
	v_add3_u32 v190, s57, v152, v153
	v_add3_u32 v192, s57, v154, v155
	v_add3_u32 v194, s57, v156, v140
	v_add_u32_e32 v195, s60, v157

.Lfm_a_exp:
	v_exp_f32_e32 v34, v34
	v_exp_f32_e32 v50, v50
	v_exp_f32_e32 v35, v35
	v_exp_f32_e32 v51, v51
	v_exp_f32_e32 v42, v42
	v_exp_f32_e32 v58, v58
	v_exp_f32_e32 v43, v43
	v_exp_f32_e32 v59, v59
	v_exp_f32_e32 v36, v36
	v_exp_f32_e32 v52, v52
	v_exp_f32_e32 v37, v37
	v_exp_f32_e32 v53, v53
	v_exp_f32_e32 v44, v44
	v_exp_f32_e32 v60, v60
	v_exp_f32_e32 v45, v45
	v_exp_f32_e32 v61, v61
	v_exp_f32_e32 v38, v38
	v_exp_f32_e32 v54, v54
	v_exp_f32_e32 v39, v39
	v_exp_f32_e32 v55, v55
	v_exp_f32_e32 v46, v46
	v_exp_f32_e32 v62, v62
	v_exp_f32_e32 v47, v47
	v_exp_f32_e32 v63, v63
	v_exp_f32_e32 v40, v40
	v_exp_f32_e32 v56, v56
	v_exp_f32_e32 v41, v41
	v_exp_f32_e32 v57, v57
	v_exp_f32_e32 v48, v48
	v_exp_f32_e32 v64, v64
	v_exp_f32_e32 v49, v49
	v_exp_f32_e32 v65, v65
	v_pk_add_f32 v[122:123], v[34:35], v[50:51]
	v_pk_add_f32 v[124:125], v[36:37], v[52:53]
	v_pk_add_f32 v[126:127], v[38:39], v[54:55]
	v_pk_add_f32 v[128:129], v[40:41], v[56:57]
	v_pk_add_f32 v[130:131], v[42:43], v[58:59]
	v_pk_add_f32 v[132:133], v[44:45], v[60:61]
	v_pk_add_f32 v[134:135], v[46:47], v[62:63]
	v_pk_add_f32 v[136:137], v[48:49], v[64:65]
	v_pk_add_f32 v[122:123], v[122:123], v[124:125]
	v_pk_add_f32 v[126:127], v[126:127], v[128:129]
	v_pk_add_f32 v[130:131], v[130:131], v[132:133]
	v_pk_add_f32 v[134:135], v[134:135], v[136:137]
	v_pk_add_f32 v[122:123], v[122:123], v[126:127]
	v_pk_add_f32 v[130:131], v[130:131], v[134:135]
	v_pk_add_f32 v[122:123], v[122:123], v[130:131]
	v_add_f32_e32 v0, v122, v123
	v_cvt_pk_bf16_f32 v122, v34, v35
	v_cvt_pk_bf16_f32 v123, v36, v37
	v_cvt_pk_bf16_f32 v124, v38, v39
	v_cvt_pk_bf16_f32 v125, v40, v41
	v_cvt_pk_bf16_f32 v126, v42, v43
	v_cvt_pk_bf16_f32 v127, v44, v45
	v_cvt_pk_bf16_f32 v128, v46, v47
	v_cvt_pk_bf16_f32 v129, v48, v49
	v_cvt_pk_bf16_f32 v130, v50, v51
	v_cvt_pk_bf16_f32 v131, v52, v53
	v_cvt_pk_bf16_f32 v132, v54, v55
	v_cvt_pk_bf16_f32 v133, v56, v57
	v_cvt_pk_bf16_f32 v134, v58, v59
	v_cvt_pk_bf16_f32 v135, v60, v61
	v_cvt_pk_bf16_f32 v136, v62, v63
	v_cvt_pk_bf16_f32 v137, v64, v65
	v_add_f32_e32 v162, v162, v0
	s_waitcnt lgkmcnt(0)
	s_barrier
	v_mfma_f32_32x32x16_bf16 v[2:17], v[164:167], v[122:125], v[2:17]
	s_setprio 1
	s_waitcnt vmcnt(3)
	ds_write_b128 v190, v[86:89]
	v_mfma_f32_32x32x16_bf16 v[18:33], v[168:171], v[122:125], v[18:33]
	ds_write_b128 v192, v[90:93]
	v_mfma_f32_32x32x16_bf16 v[2:17], v[172:175], v[126:129], v[2:17]
	ds_write_b128 v194, v[82:85] offset:13312
	v_mfma_f32_32x32x16_bf16 v[18:33], v[176:179], v[126:129], v[18:33]
	ds_read_b128 v[236:239], v195
	ds_read_b128 v[240:243], v195 offset:6656
	ds_read_b128 v[244:247], v195 offset:32
	v_mfma_f32_32x32x16_bf16 v[2:17], v[180:183], v[130:133], v[2:17]
	ds_read_b128 v[164:167], v195 offset:6688
	ds_read_b128 v[168:171], v195 offset:64
	ds_read_b128 v[172:175], v195 offset:6720
	v_mfma_f32_32x32x16_bf16 v[18:33], v[220:223], v[130:133], v[18:33]
	ds_read_b128 v[176:179], v195 offset:96
	ds_read_b128 v[180:183], v195 offset:6752
	ds_read_b128 v[220:223], v195 offset:128
	v_mfma_f32_32x32x16_bf16 v[2:17], v[224:227], v[134:137], v[2:17]
	ds_read_b128 v[224:227], v195 offset:6784
	v_mfma_f32_32x32x16_bf16 v[18:33], v[232:235], v[134:137], v[18:33]
	ds_read_b128 v[232:235], v195 offset:160
	s_waitcnt lgkmcnt(9)
	v_mfma_f32_32x32x16_bf16 v[34:49], v[236:239], v[196:199], v[66:81]
	ds_read_b128 v[236:239], v195 offset:6816
	v_mfma_f32_32x32x16_bf16 v[50:65], v[240:243], v[196:199], v[66:81]
	s_waitcnt lgkmcnt(7)
	v_mfma_f32_32x32x16_bf16 v[34:49], v[244:247], v[200:203], v[34:49]
	v_add_u32_e32 v248, s60, v160
	s_add_i32 s0, s59, 4
	s_lshl_b32 s8, s0, 6
	v_mfma_f32_32x32x16_bf16 v[50:65], v[164:167], v[200:203], v[50:65]
	ds_read_b128 v[164:167], v248 offset:13312
	s_mul_i32 s0, s8, 0x600
	s_mov_b32 s1, 0
	v_mfma_f32_32x32x16_bf16 v[34:49], v[168:171], v[204:207], v[34:49]
	ds_read_b128 v[168:171], v248 offset:17920
	v_lshl_add_u64 v[82:83], s[0:1], 0, v[186:187]
	v_lshl_add_u64 v[84:85], s[0:1], 0, v[188:189]
	s_waitcnt lgkmcnt(6)
	v_mfma_f32_32x32x16_bf16 v[50:65], v[172:175], v[204:207], v[50:65]
	ds_read_b128 v[172:175], v248 offset:13344
	global_load_dwordx4 v[86:89], v[82:83], off
	global_load_dwordx4 v[90:93], v[84:85], off
	v_mfma_f32_32x32x16_bf16 v[34:49], v[176:179], v[208:211], v[34:49]
	ds_read_b128 v[176:179], v248 offset:17952
	v_lshl_add_u64 v[82:83], s[8:9], 1, v[142:143]
	global_load_dwordx4 v[82:85], v[82:83], off
	v_mfma_f32_32x32x16_bf16 v[50:65], v[180:183], v[208:211], v[50:65]
	ds_read_b128 v[180:183], v248 offset:13376
	v_add3_u32 v190, s58, v152, v153
	v_add3_u32 v192, s58, v154, v155
	s_waitcnt lgkmcnt(6)
	v_mfma_f32_32x32x16_bf16 v[34:49], v[220:223], v[212:215], v[34:49]
	ds_read_b128 v[220:223], v248 offset:17984
	v_add3_u32 v194, s58, v156, v140
	v_add_u32_e32 v195, s57, v157
	v_mfma_f32_32x32x16_bf16 v[50:65], v[224:227], v[212:215], v[50:65]
	ds_read_b128 v[224:227], v248 offset:13408
	v_mfma_f32_32x32x16_bf16 v[34:49], v[232:235], v[216:219], v[34:49]
	ds_read_b128 v[232:235], v248 offset:18016
	s_waitcnt lgkmcnt(8)
	v_mfma_f32_32x32x16_bf16 v[50:65], v[236:239], v[216:219], v[50:65]
	s_setprio 0
	s_waitcnt lgkmcnt(8)
	s_barrier
	v_max3_f32 v0, v34, v35, v36
	v_max3_f32 v106, v50, v51, v52
	v_max3_f32 v0, v0, v37, v38
	v_max3_f32 v106, v106, v53, v54
	v_max3_f32 v0, v0, v39, v40
	v_max3_f32 v106, v106, v55, v56
	v_max3_f32 v0, v0, v41, v42
	v_max3_f32 v106, v106, v57, v58
	v_max3_f32 v0, v0, v43, v44
	v_max3_f32 v106, v106, v59, v60
	v_max3_f32 v0, v0, v45, v46
	v_max3_f32 v106, v106, v61, v62
	v_max3_f32 v0, v0, v47, v48
	v_max3_f32 v106, v106, v63, v64
	v_max3_f32 v0, v0, v106, v49
	v_max_f32_e32 v0, v0, v65
	v_cmp_lt_f32_e32 vcc, s35, v0
	s_cbranch_vccnz .Lfm_b_resc
.Lfm_b_exp:
	v_exp_f32_e32 v34, v34
	v_exp_f32_e32 v50, v50
	v_exp_f32_e32 v35, v35
	v_exp_f32_e32 v51, v51
	v_exp_f32_e32 v42, v42
	v_exp_f32_e32 v58, v58
	v_exp_f32_e32 v43, v43
	v_exp_f32_e32 v59, v59
	v_exp_f32_e32 v36, v36
	v_exp_f32_e32 v52, v52
	v_exp_f32_e32 v37, v37
	v_exp_f32_e32 v53, v53
	v_exp_f32_e32 v44, v44
	v_exp_f32_e32 v60, v60
	v_exp_f32_e32 v45, v45
	v_exp_f32_e32 v61, v61
	v_exp_f32_e32 v38, v38
	v_exp_f32_e32 v54, v54
	v_exp_f32_e32 v39, v39
	v_exp_f32_e32 v55, v55
	v_exp_f32_e32 v46, v46
	v_exp_f32_e32 v62, v62
	v_exp_f32_e32 v47, v47
	v_exp_f32_e32 v63, v63
	v_exp_f32_e32 v40, v40
	v_exp_f32_e32 v56, v56
	v_exp_f32_e32 v41, v41
	v_exp_f32_e32 v57, v57
	v_exp_f32_e32 v48, v48
	v_exp_f32_e32 v64, v64
	v_exp_f32_e32 v49, v49
	v_exp_f32_e32 v65, v65
	v_pk_add_f32 v[106:107], v[34:35], v[50:51]
	v_pk_add_f32 v[108:109], v[36:37], v[52:53]
	v_pk_add_f32 v[110:111], v[38:39], v[54:55]
	v_pk_add_f32 v[112:113], v[40:41], v[56:57]
	v_pk_add_f32 v[114:115], v[42:43], v[58:59]
	v_pk_add_f32 v[116:117], v[44:45], v[60:61]
	v_pk_add_f32 v[118:119], v[46:47], v[62:63]
	v_pk_add_f32 v[120:121], v[48:49], v[64:65]
	v_pk_add_f32 v[106:107], v[106:107], v[108:109]
	v_pk_add_f32 v[110:111], v[110:111], v[112:113]
	v_pk_add_f32 v[114:115], v[114:115], v[116:117]
	v_pk_add_f32 v[118:119], v[118:119], v[120:121]
	v_pk_add_f32 v[106:107], v[106:107], v[110:111]
	v_pk_add_f32 v[114:115], v[114:115], v[118:119]
	v_pk_add_f32 v[106:107], v[106:107], v[114:115]
	v_add_f32_e32 v0, v106, v107
	v_cvt_pk_bf16_f32 v106, v34, v35
	v_cvt_pk_bf16_f32 v107, v36, v37
	v_cvt_pk_bf16_f32 v108, v38, v39
	v_cvt_pk_bf16_f32 v109, v40, v41
	v_cvt_pk_bf16_f32 v110, v42, v43
	v_cvt_pk_bf16_f32 v111, v44, v45
	v_cvt_pk_bf16_f32 v112, v46, v47
	v_cvt_pk_bf16_f32 v113, v48, v49
	v_cvt_pk_bf16_f32 v114, v50, v51
	v_cvt_pk_bf16_f32 v115, v52, v53
	v_cvt_pk_bf16_f32 v116, v54, v55
	v_cvt_pk_bf16_f32 v117, v56, v57
	v_cvt_pk_bf16_f32 v118, v58, v59
	v_cvt_pk_bf16_f32 v119, v60, v61
	v_cvt_pk_bf16_f32 v120, v62, v63
	v_cvt_pk_bf16_f32 v121, v64, v65
	v_add_f32_e32 v162, v162, v0
	s_waitcnt lgkmcnt(0)
	s_barrier
	v_mfma_f32_32x32x16_bf16 v[2:17], v[164:167], v[106:109], v[2:17]
	s_setprio 1
	s_waitcnt vmcnt(3)
	ds_write_b128 v190, v[98:101]
	v_mfma_f32_32x32x16_bf16 v[18:33], v[168:171], v[106:109], v[18:33]
	ds_write_b128 v192, v[94:97]
	v_mfma_f32_32x32x16_bf16 v[2:17], v[172:175], v[110:113], v[2:17]
	ds_write_b128 v194, v[102:105] offset:13312
	v_mfma_f32_32x32x16_bf16 v[18:33], v[176:179], v[110:113], v[18:33]
	ds_read_b128 v[236:239], v195
	ds_read_b128 v[240:243], v195 offset:6656
	ds_read_b128 v[244:247], v195 offset:32
	v_mfma_f32_32x32x16_bf16 v[2:17], v[180:183], v[114:117], v[2:17]
	ds_read_b128 v[164:167], v195 offset:6688
	ds_read_b128 v[168:171], v195 offset:64
	ds_read_b128 v[172:175], v195 offset:6720
	v_mfma_f32_32x32x16_bf16 v[18:33], v[220:223], v[114:117], v[18:33]
	ds_read_b128 v[176:179], v195 offset:96
	ds_read_b128 v[180:183], v195 offset:6752
	ds_read_b128 v[220:223], v195 offset:128
	v_mfma_f32_32x32x16_bf16 v[2:17], v[224:227], v[118:121], v[2:17]
	ds_read_b128 v[224:227], v195 offset:6784
	v_mfma_f32_32x32x16_bf16 v[18:33], v[232:235], v[118:121], v[18:33]
	ds_read_b128 v[232:235], v195 offset:160
	s_waitcnt lgkmcnt(9)
	v_mfma_f32_32x32x16_bf16 v[34:49], v[236:239], v[196:199], v[66:81]
	ds_read_b128 v[236:239], v195 offset:6816
	s_add_i32 s59, s59, 2
	s_mov_b32 s0, s58
	v_mfma_f32_32x32x16_bf16 v[50:65], v[240:243], v[196:199], v[66:81]
	s_mov_b32 s58, s57
	s_mov_b32 s57, s60
	s_mov_b32 s60, s0
	s_waitcnt lgkmcnt(7)
	v_mfma_f32_32x32x16_bf16 v[34:49], v[244:247], v[200:203], v[34:49]
	s_addk_i32 s54, 0x80
	v_add_u32_e32 v248, s58, v160
	s_add_i32 s1, s59, 3
	s_lshl_b32 s8, s1, 6
	v_mfma_f32_32x32x16_bf16 v[50:65], v[164:167], v[200:203], v[50:65]
	ds_read_b128 v[164:167], v248 offset:13312
	s_mul_i32 s20, s8, 0x600
	s_mov_b32 s21, 0
	v_mfma_f32_32x32x16_bf16 v[34:49], v[168:171], v[204:207], v[34:49]
	ds_read_b128 v[168:171], v248 offset:17920
	v_lshl_add_u64 v[94:95], s[20:21], 0, v[186:187]
	v_lshl_add_u64 v[96:97], s[20:21], 0, v[188:189]
	s_waitcnt lgkmcnt(6)
	v_mfma_f32_32x32x16_bf16 v[50:65], v[172:175], v[204:207], v[50:65]
	ds_read_b128 v[172:175], v248 offset:13344
	v_lshl_add_u64 v[102:103], s[8:9], 1, v[142:143]
	global_load_dwordx4 v[98:101], v[94:95], off
	v_mfma_f32_32x32x16_bf16 v[34:49], v[176:179], v[208:211], v[34:49]
	ds_read_b128 v[176:179], v248 offset:17952
	s_nop 0
	global_load_dwordx4 v[94:97], v[96:97], off
	global_load_dwordx4 v[102:105], v[102:103], off
	v_mfma_f32_32x32x16_bf16 v[50:65], v[180:183], v[208:211], v[50:65]
	ds_read_b128 v[180:183], v248 offset:13376
	v_add3_u32 v190, s57, v152, v153
	v_add3_u32 v192, s57, v154, v155
	s_waitcnt lgkmcnt(6)
	v_mfma_f32_32x32x16_bf16 v[34:49], v[220:223], v[212:215], v[34:49]
	ds_read_b128 v[220:223], v248 offset:17984
	v_add3_u32 v194, s57, v156, v140
	v_add_u32_e32 v195, s60, v157
	v_mfma_f32_32x32x16_bf16 v[50:65], v[224:227], v[212:215], v[50:65]
	ds_read_b128 v[224:227], v248 offset:13408
	v_mfma_f32_32x32x16_bf16 v[34:49], v[232:235], v[216:219], v[34:49]
	ds_read_b128 v[232:235], v248 offset:18016
	s_waitcnt lgkmcnt(8)
	v_mfma_f32_32x32x16_bf16 v[50:65], v[236:239], v[216:219], v[50:65]
	s_setprio 0
	s_add_i32 s4, s55, s59
	s_cmp_lt_i32 s4, -1
	s_waitcnt lgkmcnt(8)
	s_barrier
	s_cbranch_scc1 .Lfm_head
	s_mov_b32 s0, s58
	s_mov_b32 s58, s60
	s_branch .LBB0_1037
